# sample rows post-norm step (F<4>) moved from the 64 out-proj workgroups to workgroups 64-127 after their prompt rows
# baseline (speedup 1.0000x reference)
.LBB0_719:
	s_or_b64 exec, exec, s[16:17]
	v_readlane_b32 s26, v255, 25
	s_and_b64 vcc, exec, s[34:35]
	v_readlane_b32 s27, v255, 26
	s_branch .LBB0_752
	s_mov_b32 s19, 0x40001
	s_branch .LBB0_722

.LBB0_737:
	v_readlane_b32 s16, v252, 32
	v_readlane_b32 s6, v252, 33
	s_barrier
	s_add_i32 s6, s16, s6
	s_and_b32 s6, s6, 0x1ff
	s_cmpk_gt_i32 s6, 0x1ff
	v_mbcnt_lo_u32_b32 v16, -1, 0
	v_mbcnt_hi_u32_b32 v16, -1, v16
	s_cbranch_scc1 .LBB0_752
	s_lshl_b32 s68, s28, 10
	v_readlane_b32 s36, v252, 0
	v_lshlrev_b32_e32 v18, 3, v16
	s_lshl_b64 s[20:21], s[68:69], 2
	v_readlane_b32 s48, v252, 12
	v_ashrrev_i32_e32 v19, 31, v18
	v_readlane_b32 s49, v252, 13
	s_add_u32 s20, s48, s20
	s_addc_u32 s21, s49, s21
	v_lshlrev_b64 v[20:21], 2, v[18:19]
	v_lshl_add_u64 v[12:13], s[20:21], 0, v[20:21]
	global_load_dwordx4 v[0:3], v[12:13], off offset:2064
	global_load_dwordx4 v[4:7], v[12:13], off offset:2048
	global_load_dwordx4 v[8:11], v[12:13], off offset:16
	s_nop 0
	global_load_dwordx4 v[12:15], v[12:13], off
	s_lshl_b32 s20, s6, 1
	v_readlane_b32 s28, v255, 29
	s_add_i32 s22, s20, 0x4000
	s_cmp_lg_u32 s28, 3
	v_readlane_b32 s37, v252, 1
	s_cselect_b64 s[6:7], -1, 0
	s_lshl_b32 s16, s16, 1
	v_readlane_b32 s17, v255, 5
	s_and_b32 s98, s2, 64
	s_lshl_b32 s98, s98, 4
	s_sub_i32 s17, s17, s98
	s_ashr_i32 s23, s22, 31
	s_add_i32 s19, s17, s16
	s_lshl_b64 s[36:37], s[22:23], 2
	s_lshl_b64 s[16:17], s[22:23], 12
	v_readlane_b32 s21, v255, 3
	s_add_u32 s16, s21, s16
	v_readlane_b32 s21, v255, 4
	v_lshlrev_b32_e32 v17, 2, v16
	s_addc_u32 s17, s21, s17
	v_xor_b32_e32 v114, 4, v17
	v_xor_b32_e32 v115, 8, v17
	v_xor_b32_e32 v116, 16, v17
	v_xor_b32_e32 v117, 32, v17
	v_xor_b32_e32 v118, 64, v17
	v_xor_b32_e32 v119, 0x80, v17
	v_cmp_eq_u32_e64 s[34:35], 0, v16
	v_lshlrev_b64 v[16:17], 1, v[18:19]
	v_lshl_add_u64 v[98:99], s[16:17], 0, v[20:21]
	s_lshl_b64 s[16:17], s[22:23], 11
	v_readlane_b32 s24, v254, 14
	v_lshl_add_u64 v[100:101], s[16:17], 0, v[16:17]
	s_lshl_b64 s[16:17], s[22:23], 13
	s_ashr_i32 s21, s20, 31
	v_readlane_b32 s25, v254, 15
	v_lshl_add_u64 v[102:103], s[16:17], 0, v[16:17]
	s_lshl_b64 s[16:17], s[20:21], 11
	v_lshl_add_u64 v[96:97], s[24:25], 0, v[16:17]
	v_lshl_add_u64 v[104:105], s[16:17], 0, v[16:17]
	v_readlane_b32 s38, v252, 2
	v_readlane_b32 s39, v252, 3
	v_readlane_b32 s40, v252, 4
	v_readlane_b32 s41, v252, 5
	v_readlane_b32 s42, v252, 6
	v_readlane_b32 s43, v252, 7
	v_readlane_b32 s44, v252, 8
	v_readlane_b32 s45, v252, 9
	v_readlane_b32 s46, v252, 10
	v_readlane_b32 s47, v252, 11
	v_readlane_b32 s50, v252, 14
	v_readlane_b32 s51, v252, 15
	v_readlane_b32 s29, v255, 30
	s_branch .LBB0_740

.Lf4_after_f1:
	s_sub_i32 s98, s2, 64
	s_cmpk_lt_u32 s98, 0x40
	s_cbranch_scc0 .LBB0_752
	v_readlane_b32 s6, v255, 31
	v_readlane_b32 s7, v255, 32
	v_readlane_b32 s16, v252, 32
	v_mov_b32_e32 v1, 0
	s_nop 3
	s_add_u32 s6, s10, s6
	s_addc_u32 s7, s11, s7
	s_add_u32 s6, s6, 0xef00400
	s_addc_u32 s7, s7, 0
	s_cmp_lg_u32 s16, 0
	s_cbranch_scc1 .LBB0_737
	s_mov_b32 s99, 0x8000
.Lf4_poll:
	global_load_dword v0, v1, s[6:7] sc1
	s_waitcnt vmcnt(0)
	v_readfirstlane_b32 s16, v0
	s_cmp_gt_u32 s16, 63
	s_cbranch_scc1 .Lf4_seen
	s_sleep 2
	s_sub_u32 s99, s99, 1
	s_cmp_lg_u32 s99, 0
	s_cbranch_scc1 .Lf4_poll
.Lf4_seen:
	buffer_inv sc1
	s_waitcnt vmcnt(0)
	s_branch .LBB0_737
